# final RMSNorm phase: hand-written row loop, 4 rows (32 KiB) in flight per wave in 2 batches instead of 4 iterations of 2 rows; gain vector loaded once
# baseline (speedup 1.0000x reference)
;     ...
;   const int g = (ph - 2) / 11, kq = (ph - 2) % 11;
;   int sp = 0;
; #pragma unroll
;   for (int q = 0; q < 11; ++q) sp = (kq == q) ? kSeq[q] : sp;
;   float* xout = p.out + (long)g * GT * DM;
;   u16* XB = (u16*)(ws + O_XB); float* RSTD = (float*)(ws + O_RSTD);
;   u16* SEG = (u16*)(ws + O_SEG);
;   const long SEGE = (long)GT * DM;
;   if (!((PH_MASK >> sp) & 1)) return;
;     ...
;         const int step = gridDim.x * 8;
;         for (int r = blockIdx.x * 8 + wid; r < GT; r += 2 * step) {
;           const bool two = r + step < GT;
;           float* rowa = xout + (long)r * DM; float* rowb = xout + (long)(two ? r + step : r) * DM;
;           float* wa_ = sel == 3 ? (float*)(ws + O_OP) + (long)r * DM : rowa; float* wb_ = sel == 3 ? (float*)(ws + O_OP) + (long)(r + step) * DM : rowb;
;           f32x4 va[8], vb[8], gg[8]; float ssa = 0.f, ssb = 0.f;
; #pragma unroll
;           for (int i = 0; i < 8; ++i) { va[i] = *reinterpret_cast<const f32x4*>(rowa + lane * 4 + 256 * i); vb[i] = *reinterpret_cast<const f32x4*>(rowb + lane * 4 + 256 * i);
;             gg[i] = *reinterpret_cast<const f32x4*>(p.norm_final_g + lane * 4 + 256 * i); }
.LBB0_9:
	s_add_i32 s0, s81, 0xfffe
	s_and_b32 s1, s0, 0xff
	s_mulk_i32 s1, 0x75
	s_lshr_b32 s2, s1, 8
	s_sub_i32 s2, s0, s2
	s_bfe_u32 s2, s2, 0x70001
	s_bfe_u32 s1, s1, 0x80008
	s_add_i32 s2, s2, s1
	s_bfe_u32 s1, s2, 0x50003
	v_writelane_b32 v255, s1, 29
	s_mul_i32 s1, s1, 11
	s_sub_i32 s0, s0, s1
	s_lshr_b32 s4, s2, 3
	s_and_b32 s2, s0, 0xff
	s_cmp_eq_u32 s2, 1
	s_cselect_b64 s[0:1], -1, 0
	v_cndmask_b32_e64 v0, 0, 1, s[0:1]
	s_cmp_lg_u32 s2, 2
	v_readfirstlane_b32 s0, v0
	s_cselect_b32 s0, s0, 2
	s_cmp_lg_u32 s2, 3
	s_cselect_b32 s0, s0, 4
	s_cmp_lg_u32 s2, 4
	s_cselect_b32 s0, s0, 5
	s_cmp_lg_u32 s2, 5
	s_cselect_b32 s0, s0, 7
	s_cmp_lg_u32 s2, 6
	s_cselect_b32 s0, s0, 8
	s_cmp_lg_u32 s2, 7
	s_cselect_b32 s0, s0, 9
	s_cmp_lg_u32 s2, 8
	s_cselect_b32 s0, s0, 11
	s_cmp_lg_u32 s2, 9
	s_cselect_b32 s0, s0, 12
	s_cmp_lg_u32 s2, 10
	s_cselect_b32 s55, s0, 13
	s_lshl_b32 s0, s4, 27
	s_add_u32 s0, s90, s0
	s_addc_u32 s1, s91, 0
	v_writelane_b32 v255, s0, 30
	s_mov_b64 s[4:5], 0
	v_and_b32_e32 v191, 63, v190
	v_writelane_b32 v255, s1, 31
	v_writelane_b32 v255, s4, 32
	v_ashrrev_i32_e32 v232, 6, v190
	s_mov_b64 s[0:1], -1
	v_writelane_b32 v255, s5, 33
	s_mov_b64 s[46:47], 0
	s_cmp_lt_i32 s55, 7
	v_writelane_b32 v255, s55, 34
	s_cbranch_scc1 .LBB0_143
	s_cmp_gt_i32 s55, 10
	s_mov_b64 s[4:5], -1
	s_cbranch_scc0 .LBB0_69
	s_cmp_lt_i32 s55, 12
	s_cbranch_scc1 .LBB0_55
	s_cmp_gt_i32 s55, 12
	s_cbranch_scc0 .LBB0_33
	v_readlane_b32 s0, v251, 3
	s_nop 1
	v_add_u32_e32 v0, s0, v232
	s_movk_i32 s0, 0x4000
	v_cmp_gt_i32_e32 vcc, s0, v0
	s_and_saveexec_b64 s[4:5], vcc
	s_movk_i32 s2, 0x3fff
	s_cbranch_execz .LBB0_32
	v_readlane_b32 s0, v255, 30
	v_readlane_b32 s1, v255, 31
	v_lshlrev_b32_e32 v176, 4, v191
	v_lshlrev_b32_e32 v214, 2, v224
	v_lshlrev_b32_e32 v215, 2, v223
	v_mov_b32_e32 v216, 0x358637bd
	v_mov_b32_e32 v173, 0
	v_lshl_add_u64 v[204:205], s[0:1], 0, v[176:177]
	v_lshl_add_u64 v[200:201], s[88:89], 0, v[176:177]
	s_mov_b64 s[0:1], 0x1000
	v_lshl_add_u64 v[202:203], v[200:201], 0, s[0:1]
	global_load_dwordx4 v[132:135], v[200:201], off
	global_load_dwordx4 v[136:139], v[200:201], off offset:1024
	global_load_dwordx4 v[140:143], v[200:201], off offset:2048
	global_load_dwordx4 v[144:147], v[200:201], off offset:3072
	global_load_dwordx4 v[148:151], v[202:203], off
	global_load_dwordx4 v[152:155], v[202:203], off offset:1024
	global_load_dwordx4 v[156:159], v[202:203], off offset:2048
	global_load_dwordx4 v[160:163], v[202:203], off offset:3072
	s_mov_b32 s2, 0
.Lfn_batch:
	v_mov_b32_e32 v172, v0
	v_lshlrev_b64 v[164:165], 13, v[172:173]
	v_lshl_add_u64 v[164:165], v[204:205], 0, v[164:165]
	v_lshl_add_u64 v[192:193], v[164:165], 0, s[0:1]
	global_load_dwordx4 v[4:7], v[164:165], off
	global_load_dwordx4 v[8:11], v[164:165], off offset:1024
	global_load_dwordx4 v[12:15], v[164:165], off offset:2048
	global_load_dwordx4 v[16:19], v[164:165], off offset:3072
	global_load_dwordx4 v[20:23], v[192:193], off
	global_load_dwordx4 v[24:27], v[192:193], off offset:1024
	global_load_dwordx4 v[28:31], v[192:193], off offset:2048
	global_load_dwordx4 v[32:35], v[192:193], off offset:3072
	v_add_u32_e32 v172, 0x800, v0
	v_lshlrev_b64 v[166:167], 13, v[172:173]
	v_lshl_add_u64 v[166:167], v[204:205], 0, v[166:167]
	v_lshl_add_u64 v[194:195], v[166:167], 0, s[0:1]
	global_load_dwordx4 v[36:39], v[166:167], off
	global_load_dwordx4 v[40:43], v[166:167], off offset:1024
	global_load_dwordx4 v[44:47], v[166:167], off offset:2048
	global_load_dwordx4 v[48:51], v[166:167], off offset:3072
	global_load_dwordx4 v[52:55], v[194:195], off
	global_load_dwordx4 v[56:59], v[194:195], off offset:1024
	global_load_dwordx4 v[60:63], v[194:195], off offset:2048
	global_load_dwordx4 v[64:67], v[194:195], off offset:3072
	v_add_u32_e32 v172, 0x1000, v0
	v_lshlrev_b64 v[168:169], 13, v[172:173]
	v_lshl_add_u64 v[168:169], v[204:205], 0, v[168:169]
	v_lshl_add_u64 v[196:197], v[168:169], 0, s[0:1]
	global_load_dwordx4 v[68:71], v[168:169], off
	global_load_dwordx4 v[72:75], v[168:169], off offset:1024
	global_load_dwordx4 v[76:79], v[168:169], off offset:2048
	global_load_dwordx4 v[80:83], v[168:169], off offset:3072
	global_load_dwordx4 v[84:87], v[196:197], off
	global_load_dwordx4 v[88:91], v[196:197], off offset:1024
	global_load_dwordx4 v[92:95], v[196:197], off offset:2048
	global_load_dwordx4 v[96:99], v[196:197], off offset:3072
	v_add_u32_e32 v172, 0x1800, v0
	v_lshlrev_b64 v[170:171], 13, v[172:173]
	v_lshl_add_u64 v[170:171], v[204:205], 0, v[170:171]
	v_lshl_add_u64 v[198:199], v[170:171], 0, s[0:1]
	global_load_dwordx4 v[100:103], v[170:171], off
	global_load_dwordx4 v[104:107], v[170:171], off offset:1024
	global_load_dwordx4 v[108:111], v[170:171], off offset:2048
	global_load_dwordx4 v[112:115], v[170:171], off offset:3072
	global_load_dwordx4 v[116:119], v[198:199], off
	global_load_dwordx4 v[120:123], v[198:199], off offset:1024
	global_load_dwordx4 v[124:127], v[198:199], off offset:2048
	global_load_dwordx4 v[128:131], v[198:199], off offset:3072
	s_waitcnt vmcnt(0)
; DI float wave_sum(float v) {
; #pragma unroll
;   for (int o = 32; o > 0; o >>= 1) v += __shfl_xor(v, o, 64);
;   return v;
; }
;     ...
; #pragma unroll
;           for (int i = 0; i < 8; ++i) { ssa += va[i][0] * va[i][0] + va[i][1] * va[i][1] + va[i][2] * va[i][2] + va[i][3] * va[i][3]; ssb += vb[i][0] * vb[i][0] + vb[i][1] * vb[i][1] + vb[i][2] * vb[i][2] + vb[i][3] * vb[i][3]; }
;           ssa = wave_sum(ssa); ssb = wave_sum(ssb);
	v_pk_mul_f32 v[206:207], v[4:5], v[4:5]
	v_pk_mul_f32 v[208:209], v[36:37], v[36:37]
	v_pk_mul_f32 v[210:211], v[68:69], v[68:69]
	v_pk_mul_f32 v[212:213], v[100:101], v[100:101]
	v_pk_fma_f32 v[206:207], v[6:7], v[6:7], v[206:207]
	v_pk_fma_f32 v[208:209], v[38:39], v[38:39], v[208:209]
	v_pk_fma_f32 v[210:211], v[70:71], v[70:71], v[210:211]
	v_pk_fma_f32 v[212:213], v[102:103], v[102:103], v[212:213]
	v_pk_fma_f32 v[206:207], v[8:9], v[8:9], v[206:207]
	v_pk_fma_f32 v[208:209], v[40:41], v[40:41], v[208:209]
	v_pk_fma_f32 v[210:211], v[72:73], v[72:73], v[210:211]
	v_pk_fma_f32 v[212:213], v[104:105], v[104:105], v[212:213]
	v_pk_fma_f32 v[206:207], v[10:11], v[10:11], v[206:207]
	v_pk_fma_f32 v[208:209], v[42:43], v[42:43], v[208:209]
	v_pk_fma_f32 v[210:211], v[74:75], v[74:75], v[210:211]
	v_pk_fma_f32 v[212:213], v[106:107], v[106:107], v[212:213]
	v_pk_fma_f32 v[206:207], v[12:13], v[12:13], v[206:207]
	v_pk_fma_f32 v[208:209], v[44:45], v[44:45], v[208:209]
	v_pk_fma_f32 v[210:211], v[76:77], v[76:77], v[210:211]
	v_pk_fma_f32 v[212:213], v[108:109], v[108:109], v[212:213]
	v_pk_fma_f32 v[206:207], v[14:15], v[14:15], v[206:207]
	v_pk_fma_f32 v[208:209], v[46:47], v[46:47], v[208:209]
	v_pk_fma_f32 v[210:211], v[78:79], v[78:79], v[210:211]
	v_pk_fma_f32 v[212:213], v[110:111], v[110:111], v[212:213]
	v_pk_fma_f32 v[206:207], v[16:17], v[16:17], v[206:207]
	v_pk_fma_f32 v[208:209], v[48:49], v[48:49], v[208:209]
	v_pk_fma_f32 v[210:211], v[80:81], v[80:81], v[210:211]
	v_pk_fma_f32 v[212:213], v[112:113], v[112:113], v[212:213]
	v_pk_fma_f32 v[206:207], v[18:19], v[18:19], v[206:207]
	v_pk_fma_f32 v[208:209], v[50:51], v[50:51], v[208:209]
	v_pk_fma_f32 v[210:211], v[82:83], v[82:83], v[210:211]
	v_pk_fma_f32 v[212:213], v[114:115], v[114:115], v[212:213]
	v_pk_fma_f32 v[206:207], v[20:21], v[20:21], v[206:207]
	v_pk_fma_f32 v[208:209], v[52:53], v[52:53], v[208:209]
	v_pk_fma_f32 v[210:211], v[84:85], v[84:85], v[210:211]
	v_pk_fma_f32 v[212:213], v[116:117], v[116:117], v[212:213]
	v_pk_fma_f32 v[206:207], v[22:23], v[22:23], v[206:207]
	v_pk_fma_f32 v[208:209], v[54:55], v[54:55], v[208:209]
	v_pk_fma_f32 v[210:211], v[86:87], v[86:87], v[210:211]
	v_pk_fma_f32 v[212:213], v[118:119], v[118:119], v[212:213]
	v_pk_fma_f32 v[206:207], v[24:25], v[24:25], v[206:207]
	v_pk_fma_f32 v[208:209], v[56:57], v[56:57], v[208:209]
	v_pk_fma_f32 v[210:211], v[88:89], v[88:89], v[210:211]
	v_pk_fma_f32 v[212:213], v[120:121], v[120:121], v[212:213]
	v_pk_fma_f32 v[206:207], v[26:27], v[26:27], v[206:207]
	v_pk_fma_f32 v[208:209], v[58:59], v[58:59], v[208:209]
	v_pk_fma_f32 v[210:211], v[90:91], v[90:91], v[210:211]
	v_pk_fma_f32 v[212:213], v[122:123], v[122:123], v[212:213]
	v_pk_fma_f32 v[206:207], v[28:29], v[28:29], v[206:207]
	v_pk_fma_f32 v[208:209], v[60:61], v[60:61], v[208:209]
	v_pk_fma_f32 v[210:211], v[92:93], v[92:93], v[210:211]
	v_pk_fma_f32 v[212:213], v[124:125], v[124:125], v[212:213]
	v_pk_fma_f32 v[206:207], v[30:31], v[30:31], v[206:207]
	v_pk_fma_f32 v[208:209], v[62:63], v[62:63], v[208:209]
	v_pk_fma_f32 v[210:211], v[94:95], v[94:95], v[210:211]
	v_pk_fma_f32 v[212:213], v[126:127], v[126:127], v[212:213]
	v_pk_fma_f32 v[206:207], v[32:33], v[32:33], v[206:207]
	v_pk_fma_f32 v[208:209], v[64:65], v[64:65], v[208:209]
	v_pk_fma_f32 v[210:211], v[96:97], v[96:97], v[210:211]
	v_pk_fma_f32 v[212:213], v[128:129], v[128:129], v[212:213]
	v_pk_fma_f32 v[206:207], v[34:35], v[34:35], v[206:207]
	v_pk_fma_f32 v[208:209], v[66:67], v[66:67], v[208:209]
	v_pk_fma_f32 v[210:211], v[98:99], v[98:99], v[210:211]
	v_pk_fma_f32 v[212:213], v[130:131], v[130:131], v[212:213]
	s_nop 0
	v_add_f32_e32 v206, v206, v207
	v_add_f32_e32 v208, v208, v209
	v_add_f32_e32 v210, v210, v211
	v_add_f32_e32 v212, v212, v213
	s_nop 0
	v_add_f32_dpp v206, v206, v206 quad_perm:[1,0,3,2] row_mask:0xf bank_mask:0xf
	v_add_f32_dpp v208, v208, v208 quad_perm:[1,0,3,2] row_mask:0xf bank_mask:0xf
	v_add_f32_dpp v210, v210, v210 quad_perm:[1,0,3,2] row_mask:0xf bank_mask:0xf
	v_add_f32_dpp v212, v212, v212 quad_perm:[1,0,3,2] row_mask:0xf bank_mask:0xf
	s_nop 0
	v_add_f32_dpp v206, v206, v206 quad_perm:[2,3,0,1] row_mask:0xf bank_mask:0xf
	v_add_f32_dpp v208, v208, v208 quad_perm:[2,3,0,1] row_mask:0xf bank_mask:0xf
	v_add_f32_dpp v210, v210, v210 quad_perm:[2,3,0,1] row_mask:0xf bank_mask:0xf
	v_add_f32_dpp v212, v212, v212 quad_perm:[2,3,0,1] row_mask:0xf bank_mask:0xf
	s_nop 0
	v_add_f32_dpp v206, v206, v206 row_half_mirror row_mask:0xf bank_mask:0xf
	v_add_f32_dpp v208, v208, v208 row_half_mirror row_mask:0xf bank_mask:0xf
	v_add_f32_dpp v210, v210, v210 row_half_mirror row_mask:0xf bank_mask:0xf
	v_add_f32_dpp v212, v212, v212 row_half_mirror row_mask:0xf bank_mask:0xf
	s_nop 0
	v_add_f32_dpp v206, v206, v206 row_mirror row_mask:0xf bank_mask:0xf
	v_add_f32_dpp v208, v208, v208 row_mirror row_mask:0xf bank_mask:0xf
	v_add_f32_dpp v210, v210, v210 row_mirror row_mask:0xf bank_mask:0xf
	v_add_f32_dpp v212, v212, v212 row_mirror row_mask:0xf bank_mask:0xf
	ds_bpermute_b32 v207, v214, v206
	ds_bpermute_b32 v209, v214, v208
	ds_bpermute_b32 v211, v214, v210
	ds_bpermute_b32 v213, v214, v212
	s_waitcnt lgkmcnt(0)
	v_add_f32_e32 v206, v206, v207
	v_add_f32_e32 v208, v208, v209
	v_add_f32_e32 v210, v210, v211
	v_add_f32_e32 v212, v212, v213
	ds_bpermute_b32 v207, v215, v206
	ds_bpermute_b32 v209, v215, v208
	ds_bpermute_b32 v211, v215, v210
	ds_bpermute_b32 v213, v215, v212
	s_waitcnt lgkmcnt(0)
;     ...
;           const float ra = rsqrtf(ssa * (1.f / 2048.f) + 1e-6f), rb = rsqrtf(ssb * (1.f / 2048.f) + 1e-6f);
; #pragma unroll
;           for (int i = 0; i < 8; ++i) {
;             *reinterpret_cast<f32x4*>(wa_ + lane * 4 + 256 * i) = va[i] * gg[i] * ra;
;             if (two) *reinterpret_cast<f32x4*>(wb_ + lane * 4 + 256 * i) = vb[i] * gg[i] * rb;
;           }
	v_add_f32_e32 v206, v206, v207
	v_add_f32_e32 v208, v208, v209
	v_add_f32_e32 v210, v210, v211
	v_add_f32_e32 v212, v212, v213
	v_fmamk_f32 v206, v206, 0x3a000000, v216
	v_fmamk_f32 v208, v208, 0x3a000000, v216
	v_fmamk_f32 v210, v210, 0x3a000000, v216
	v_fmamk_f32 v212, v212, 0x3a000000, v216
	v_rsq_f32_e32 v206, v206
	v_rsq_f32_e32 v208, v208
	v_rsq_f32_e32 v210, v210
	v_rsq_f32_e32 v212, v212
	v_pk_mul_f32 v[4:5], v[4:5], v[132:133]
	v_pk_mul_f32 v[6:7], v[6:7], v[134:135]
	v_pk_mul_f32 v[36:37], v[36:37], v[132:133]
	v_pk_mul_f32 v[38:39], v[38:39], v[134:135]
	v_pk_mul_f32 v[68:69], v[68:69], v[132:133]
	v_pk_mul_f32 v[70:71], v[70:71], v[134:135]
	v_pk_mul_f32 v[100:101], v[100:101], v[132:133]
	v_pk_mul_f32 v[102:103], v[102:103], v[134:135]
	v_pk_mul_f32 v[4:5], v[4:5], v[206:207] op_sel_hi:[1,0]
	v_pk_mul_f32 v[6:7], v[6:7], v[206:207] op_sel_hi:[1,0]
	v_pk_mul_f32 v[36:37], v[36:37], v[208:209] op_sel_hi:[1,0]
	v_pk_mul_f32 v[38:39], v[38:39], v[208:209] op_sel_hi:[1,0]
	v_pk_mul_f32 v[68:69], v[68:69], v[210:211] op_sel_hi:[1,0]
	v_pk_mul_f32 v[70:71], v[70:71], v[210:211] op_sel_hi:[1,0]
	v_pk_mul_f32 v[100:101], v[100:101], v[212:213] op_sel_hi:[1,0]
	v_pk_mul_f32 v[102:103], v[102:103], v[212:213] op_sel_hi:[1,0]
	global_store_dwordx4 v[164:165], v[4:7], off
	global_store_dwordx4 v[166:167], v[36:39], off
	global_store_dwordx4 v[168:169], v[68:71], off
	global_store_dwordx4 v[170:171], v[100:103], off
	v_pk_mul_f32 v[8:9], v[8:9], v[136:137]
	v_pk_mul_f32 v[10:11], v[10:11], v[138:139]
	v_pk_mul_f32 v[40:41], v[40:41], v[136:137]
	v_pk_mul_f32 v[42:43], v[42:43], v[138:139]
	v_pk_mul_f32 v[72:73], v[72:73], v[136:137]
	v_pk_mul_f32 v[74:75], v[74:75], v[138:139]
	v_pk_mul_f32 v[104:105], v[104:105], v[136:137]
	v_pk_mul_f32 v[106:107], v[106:107], v[138:139]
	v_pk_mul_f32 v[8:9], v[8:9], v[206:207] op_sel_hi:[1,0]
	v_pk_mul_f32 v[10:11], v[10:11], v[206:207] op_sel_hi:[1,0]
	v_pk_mul_f32 v[40:41], v[40:41], v[208:209] op_sel_hi:[1,0]
	v_pk_mul_f32 v[42:43], v[42:43], v[208:209] op_sel_hi:[1,0]
	v_pk_mul_f32 v[72:73], v[72:73], v[210:211] op_sel_hi:[1,0]
	v_pk_mul_f32 v[74:75], v[74:75], v[210:211] op_sel_hi:[1,0]
	v_pk_mul_f32 v[104:105], v[104:105], v[212:213] op_sel_hi:[1,0]
	v_pk_mul_f32 v[106:107], v[106:107], v[212:213] op_sel_hi:[1,0]
	global_store_dwordx4 v[164:165], v[8:11], off offset:1024
	global_store_dwordx4 v[166:167], v[40:43], off offset:1024
	global_store_dwordx4 v[168:169], v[72:75], off offset:1024
	global_store_dwordx4 v[170:171], v[104:107], off offset:1024
	v_pk_mul_f32 v[12:13], v[12:13], v[140:141]
	v_pk_mul_f32 v[14:15], v[14:15], v[142:143]
	v_pk_mul_f32 v[44:45], v[44:45], v[140:141]
	v_pk_mul_f32 v[46:47], v[46:47], v[142:143]
	v_pk_mul_f32 v[76:77], v[76:77], v[140:141]
	v_pk_mul_f32 v[78:79], v[78:79], v[142:143]
	v_pk_mul_f32 v[108:109], v[108:109], v[140:141]
	v_pk_mul_f32 v[110:111], v[110:111], v[142:143]
	v_pk_mul_f32 v[12:13], v[12:13], v[206:207] op_sel_hi:[1,0]
	v_pk_mul_f32 v[14:15], v[14:15], v[206:207] op_sel_hi:[1,0]
	v_pk_mul_f32 v[44:45], v[44:45], v[208:209] op_sel_hi:[1,0]
	v_pk_mul_f32 v[46:47], v[46:47], v[208:209] op_sel_hi:[1,0]
	v_pk_mul_f32 v[76:77], v[76:77], v[210:211] op_sel_hi:[1,0]
	v_pk_mul_f32 v[78:79], v[78:79], v[210:211] op_sel_hi:[1,0]
	v_pk_mul_f32 v[108:109], v[108:109], v[212:213] op_sel_hi:[1,0]
	v_pk_mul_f32 v[110:111], v[110:111], v[212:213] op_sel_hi:[1,0]
	global_store_dwordx4 v[164:165], v[12:15], off offset:2048
	global_store_dwordx4 v[166:167], v[44:47], off offset:2048
	global_store_dwordx4 v[168:169], v[76:79], off offset:2048
	global_store_dwordx4 v[170:171], v[108:111], off offset:2048
	v_pk_mul_f32 v[16:17], v[16:17], v[144:145]
	v_pk_mul_f32 v[18:19], v[18:19], v[146:147]
	v_pk_mul_f32 v[48:49], v[48:49], v[144:145]
	v_pk_mul_f32 v[50:51], v[50:51], v[146:147]
	v_pk_mul_f32 v[80:81], v[80:81], v[144:145]
	v_pk_mul_f32 v[82:83], v[82:83], v[146:147]
	v_pk_mul_f32 v[112:113], v[112:113], v[144:145]
	v_pk_mul_f32 v[114:115], v[114:115], v[146:147]
	v_pk_mul_f32 v[16:17], v[16:17], v[206:207] op_sel_hi:[1,0]
	v_pk_mul_f32 v[18:19], v[18:19], v[206:207] op_sel_hi:[1,0]
	v_pk_mul_f32 v[48:49], v[48:49], v[208:209] op_sel_hi:[1,0]
	v_pk_mul_f32 v[50:51], v[50:51], v[208:209] op_sel_hi:[1,0]
	v_pk_mul_f32 v[80:81], v[80:81], v[210:211] op_sel_hi:[1,0]
	v_pk_mul_f32 v[82:83], v[82:83], v[210:211] op_sel_hi:[1,0]
	v_pk_mul_f32 v[112:113], v[112:113], v[212:213] op_sel_hi:[1,0]
	v_pk_mul_f32 v[114:115], v[114:115], v[212:213] op_sel_hi:[1,0]
	global_store_dwordx4 v[164:165], v[16:19], off offset:3072
	global_store_dwordx4 v[166:167], v[48:51], off offset:3072
;     ...
;         for (int r = blockIdx.x * 8 + wid; r < GT; r += 2 * step) {
;     ...
; #pragma unroll
;           for (int i = 0; i < 8; ++i) {
;             *reinterpret_cast<f32x4*>(wa_ + lane * 4 + 256 * i) = va[i] * gg[i] * ra;
;             if (two) *reinterpret_cast<f32x4*>(wb_ + lane * 4 + 256 * i) = vb[i] * gg[i] * rb;
;           }
	global_store_dwordx4 v[168:169], v[80:83], off offset:3072
	global_store_dwordx4 v[170:171], v[112:115], off offset:3072
	v_pk_mul_f32 v[20:21], v[20:21], v[148:149]
	v_pk_mul_f32 v[22:23], v[22:23], v[150:151]
	v_pk_mul_f32 v[52:53], v[52:53], v[148:149]
	v_pk_mul_f32 v[54:55], v[54:55], v[150:151]
	v_pk_mul_f32 v[84:85], v[84:85], v[148:149]
	v_pk_mul_f32 v[86:87], v[86:87], v[150:151]
	v_pk_mul_f32 v[116:117], v[116:117], v[148:149]
	v_pk_mul_f32 v[118:119], v[118:119], v[150:151]
	v_pk_mul_f32 v[20:21], v[20:21], v[206:207] op_sel_hi:[1,0]
	v_pk_mul_f32 v[22:23], v[22:23], v[206:207] op_sel_hi:[1,0]
	v_pk_mul_f32 v[52:53], v[52:53], v[208:209] op_sel_hi:[1,0]
	v_pk_mul_f32 v[54:55], v[54:55], v[208:209] op_sel_hi:[1,0]
	v_pk_mul_f32 v[84:85], v[84:85], v[210:211] op_sel_hi:[1,0]
	v_pk_mul_f32 v[86:87], v[86:87], v[210:211] op_sel_hi:[1,0]
	v_pk_mul_f32 v[116:117], v[116:117], v[212:213] op_sel_hi:[1,0]
	v_pk_mul_f32 v[118:119], v[118:119], v[212:213] op_sel_hi:[1,0]
	global_store_dwordx4 v[192:193], v[20:23], off
	global_store_dwordx4 v[194:195], v[52:55], off
	global_store_dwordx4 v[196:197], v[84:87], off
	global_store_dwordx4 v[198:199], v[116:119], off
	v_pk_mul_f32 v[24:25], v[24:25], v[152:153]
	v_pk_mul_f32 v[26:27], v[26:27], v[154:155]
	v_pk_mul_f32 v[56:57], v[56:57], v[152:153]
	v_pk_mul_f32 v[58:59], v[58:59], v[154:155]
	v_pk_mul_f32 v[88:89], v[88:89], v[152:153]
	v_pk_mul_f32 v[90:91], v[90:91], v[154:155]
	v_pk_mul_f32 v[120:121], v[120:121], v[152:153]
	v_pk_mul_f32 v[122:123], v[122:123], v[154:155]
	v_pk_mul_f32 v[24:25], v[24:25], v[206:207] op_sel_hi:[1,0]
	v_pk_mul_f32 v[26:27], v[26:27], v[206:207] op_sel_hi:[1,0]
	v_pk_mul_f32 v[56:57], v[56:57], v[208:209] op_sel_hi:[1,0]
	v_pk_mul_f32 v[58:59], v[58:59], v[208:209] op_sel_hi:[1,0]
	v_pk_mul_f32 v[88:89], v[88:89], v[210:211] op_sel_hi:[1,0]
	v_pk_mul_f32 v[90:91], v[90:91], v[210:211] op_sel_hi:[1,0]
	v_pk_mul_f32 v[120:121], v[120:121], v[212:213] op_sel_hi:[1,0]
	v_pk_mul_f32 v[122:123], v[122:123], v[212:213] op_sel_hi:[1,0]
	global_store_dwordx4 v[192:193], v[24:27], off offset:1024
	global_store_dwordx4 v[194:195], v[56:59], off offset:1024
	global_store_dwordx4 v[196:197], v[88:91], off offset:1024
	global_store_dwordx4 v[198:199], v[120:123], off offset:1024
	v_pk_mul_f32 v[28:29], v[28:29], v[156:157]
	v_pk_mul_f32 v[30:31], v[30:31], v[158:159]
	v_pk_mul_f32 v[60:61], v[60:61], v[156:157]
	v_pk_mul_f32 v[62:63], v[62:63], v[158:159]
	v_pk_mul_f32 v[92:93], v[92:93], v[156:157]
	v_pk_mul_f32 v[94:95], v[94:95], v[158:159]
	v_pk_mul_f32 v[124:125], v[124:125], v[156:157]
	v_pk_mul_f32 v[126:127], v[126:127], v[158:159]
	v_pk_mul_f32 v[28:29], v[28:29], v[206:207] op_sel_hi:[1,0]
	v_pk_mul_f32 v[30:31], v[30:31], v[206:207] op_sel_hi:[1,0]
	v_pk_mul_f32 v[60:61], v[60:61], v[208:209] op_sel_hi:[1,0]
	v_pk_mul_f32 v[62:63], v[62:63], v[208:209] op_sel_hi:[1,0]
	v_pk_mul_f32 v[92:93], v[92:93], v[210:211] op_sel_hi:[1,0]
	v_pk_mul_f32 v[94:95], v[94:95], v[210:211] op_sel_hi:[1,0]
	v_pk_mul_f32 v[124:125], v[124:125], v[212:213] op_sel_hi:[1,0]
	v_pk_mul_f32 v[126:127], v[126:127], v[212:213] op_sel_hi:[1,0]
	global_store_dwordx4 v[192:193], v[28:31], off offset:2048
	global_store_dwordx4 v[194:195], v[60:63], off offset:2048
	global_store_dwordx4 v[196:197], v[92:95], off offset:2048
	global_store_dwordx4 v[198:199], v[124:127], off offset:2048
	v_pk_mul_f32 v[32:33], v[32:33], v[160:161]
	v_pk_mul_f32 v[34:35], v[34:35], v[162:163]
	v_pk_mul_f32 v[64:65], v[64:65], v[160:161]
	v_pk_mul_f32 v[66:67], v[66:67], v[162:163]
	v_pk_mul_f32 v[96:97], v[96:97], v[160:161]
	v_pk_mul_f32 v[98:99], v[98:99], v[162:163]
	v_pk_mul_f32 v[128:129], v[128:129], v[160:161]
	v_pk_mul_f32 v[130:131], v[130:131], v[162:163]
	v_pk_mul_f32 v[32:33], v[32:33], v[206:207] op_sel_hi:[1,0]
	v_pk_mul_f32 v[34:35], v[34:35], v[206:207] op_sel_hi:[1,0]
	v_pk_mul_f32 v[64:65], v[64:65], v[208:209] op_sel_hi:[1,0]
	v_pk_mul_f32 v[66:67], v[66:67], v[208:209] op_sel_hi:[1,0]
	v_pk_mul_f32 v[96:97], v[96:97], v[210:211] op_sel_hi:[1,0]
	v_pk_mul_f32 v[98:99], v[98:99], v[210:211] op_sel_hi:[1,0]
	v_pk_mul_f32 v[128:129], v[128:129], v[212:213] op_sel_hi:[1,0]
	v_pk_mul_f32 v[130:131], v[130:131], v[212:213] op_sel_hi:[1,0]
	global_store_dwordx4 v[192:193], v[32:35], off offset:3072
	global_store_dwordx4 v[194:195], v[64:67], off offset:3072
	global_store_dwordx4 v[196:197], v[96:99], off offset:3072
	global_store_dwordx4 v[198:199], v[128:131], off offset:3072
	s_add_i32 s2, s2, 1
	v_add_u32_e32 v0, 0x2000, v0
	s_cmp_lt_u32 s2, 2
	s_cbranch_scc1 .Lfn_batch
